# GEMM tail overlap extended to layer-1 PH7+PH8: the two ACT tiles of M-tiles 256/257 are stored in the dead layer-0 weight region instead of d_out scratch so the tail tiles can run while the final rows
# speedup vs baseline: 1.0161x; 1.0063x over previous
; __device__ __forceinline__ void st8(bf16_t* p, f32x4 a, f32x4 b) { u32x4 w; w.x = cvt_pk_bf16(a[0], a[1]); w.y = cvt_pk_bf16(a[2], a[3]); w.z = cvt_pk_bf16(b[0], b[1]); w.w = cvt_pk_bf16(b[2], b[3]); *(u32x4*)p = w; }
;     __device__ __forceinline__ void operator()(const f32x4 (&acc)[2][2][4][2], const Unit& u, int wr, int wc, int fr, int fq) const {
;         asm volatile("" : "+v"(fr), "+v"(fq)); asm volatile("" : "+s"(wr), "+s"(wc));
;         const int rl0 = wr * 64 + fr, pn = u.pn, cw = wc * 32 + fq * 8;
;         bf16_t* base = (u.pm < pm_split) ? ACT1 + (size_t)u.pm * BM * 2816 : ACT2 + (size_t)(u.pm - pm_split) * BM * 2816;
; #pragma unroll
;         for (int ai = 0; ai < 2; ++ai)
; #pragma unroll
;             for (int m = 0; m < 4; ++m) {
;                 const int rl = rl0 + ai * HALF + m * 16;
;                 const float s = rsqrtf(ssqX[u.pm * BM + rl] * (1.0f / 1024.0f) + EPS);
;                 f32x4 o[2];
; #pragma unroll
;                 for (int n = 0; n < 2; ++n) {
;                     const f32x4 g = acc[ai][0][m][n] * s, up = acc[ai][1][m][n] * s;
; #pragma unroll
;                     for (int j = 0; j < 4; ++j) { const float e = __builtin_amdgcn_exp2f(g[j] * -1.4426950408889634f); o[n][j] = g[j] * __builtin_amdgcn_rcpf(1.0f + e) * up[j]; }
;                 }
;                 st8(base + (size_t)rl * 2816 + pn * 128 + cw, o[0], o[1]);
;                 asm volatile("" ::: "memory");
;             }
.LBB0_1615:
	s_add_i32 s23, s28, 0xffffff76
	s_ashr_i32 s30, s28, 31
	s_cmpk_lt_i32 s28, 0x8a
	s_cselect_b32 s23, s28, s23
	s_cselect_b32 s30, s30, 0
	s_mul_i32 s30, s30, 0x160000
	s_mul_hi_u32 s35, s23, 0x160000
	v_mov_b32_e32 v151, v144
	v_mov_b32_e32 v156, v145
	s_mov_b32 s5, s52
	s_mov_b32 s4, s42
	s_cselect_b32 s31, s49, s7
	s_cselect_b32 s34, s48, s6
	s_sub_u32 s84, s92, 0xa140000
	s_subb_u32 s85, s93, 0
	s_cmpk_gt_i32 s28, 0xff
	s_cselect_b32 s34, s84, s34
	s_cselect_b32 s31, s85, s31
	s_add_i32 s35, s35, s30
	s_mul_i32 s23, s23, 0x160000
	s_add_u32 s23, s34, s23
	s_addc_u32 s34, s31, s35
	v_lshl_add_u32 v151, s4, 6, v151
	s_lshl_b32 s4, s28, 8
	v_add_u32_e32 v152, s4, v151
	v_ashrrev_i32_e32 v153, 31, v152
	v_lshl_add_u64 v[152:153], v[152:153], 2, s[14:15]
	global_load_dword v157, v[152:153], off
	v_mov_b32_e32 v154, v122
	v_mov_b32_e32 v155, v114
	v_mov_b32_e32 v114, v123
	v_mov_b32_e32 v152, v124
	v_mov_b32_e32 v124, v126
	v_mov_b32_e32 v126, v120
	v_lshlrev_b32_e32 v120, 3, v156
	v_mov_b32_e32 v153, v116
	v_mov_b32_e32 v116, v125
	v_mov_b32_e32 v125, v118
	v_mov_b32_e32 v118, v127
	v_mov_b32_e32 v127, v112
	v_mov_b32_e32 v112, v121
	s_lshl_b32 s30, s61, 7
	s_ashr_i32 s31, s30, 31
	s_lshl_b64 s[30:31], s[30:31], 1
	v_lshl_add_u32 v120, s5, 5, v120
	s_add_u32 s30, s23, s30
	v_ashrrev_i32_e32 v121, 31, v120
	s_addc_u32 s31, s34, s31
	v_lshl_add_u64 v[120:121], v[120:121], 1, s[30:31]
	s_waitcnt vmcnt(0)
	v_fmamk_f32 v122, v157, 0x3a800000, v150
	v_mul_f32_e32 v123, 0x4b800000, v122
	v_cmp_gt_f32_e32 vcc, s58, v122
	s_nop 1
	v_cndmask_b32_e32 v122, v122, v123, vcc
	v_rsq_f32_e32 v156, v122
	v_mad_i64_i32 v[122:123], s[30:31], v151, s59, v[120:121]
	v_mul_f32_e32 v157, 0x45800000, v156
	v_cndmask_b32_e32 v156, v156, v157, vcc
	v_pk_mul_f32 v[152:153], v[152:153], v[156:157] op_sel_hi:[1,0]
	v_pk_mul_f32 v[116:117], v[116:117], v[156:157] op_sel_hi:[1,0]
	v_pk_mul_f32 v[124:125], v[124:125], v[156:157] op_sel_hi:[1,0]
	v_pk_mul_f32 v[118:119], v[118:119], v[156:157] op_sel_hi:[1,0]
	v_pk_mul_f32 v[126:127], v[126:127], v[156:157] op_sel_hi:[1,0]
	v_pk_mul_f32 v[112:113], v[112:113], v[156:157] op_sel_hi:[1,0]
	v_pk_mul_f32 v[114:115], v[114:115], v[156:157] op_sel_hi:[1,0]
	v_pk_mul_f32 v[154:155], v[154:155], v[156:157] op_sel_hi:[1,0]
	v_mul_f32_e32 v156, 0xbfb8aa3b, v153
	v_mul_f32_e32 v157, 0xbfb8aa3b, v117
	v_mul_f32_e32 v158, 0xbfb8aa3b, v125
	v_mul_f32_e32 v159, 0xbfb8aa3b, v119
	v_mul_f32_e32 v160, 0xbfb8aa3b, v127
	v_mul_f32_e32 v161, 0xbfb8aa3b, v113
	v_mul_f32_e32 v163, 0xbfb8aa3b, v115
	v_mul_f32_e32 v162, 0xbfb8aa3b, v155
	v_exp_f32_e32 v156, v156
	v_exp_f32_e32 v157, v157
	v_exp_f32_e32 v158, v158
	v_exp_f32_e32 v159, v159
	v_exp_f32_e32 v160, v160
	v_exp_f32_e32 v161, v161
	v_exp_f32_e32 v163, v163
	v_exp_f32_e32 v162, v162
	v_add_f32_e32 v156, 1.0, v156
	v_add_f32_e32 v157, 1.0, v157
	v_add_f32_e32 v158, 1.0, v158
	v_add_f32_e32 v159, 1.0, v159
	v_add_f32_e32 v160, 1.0, v160
	v_add_f32_e32 v161, 1.0, v161
	v_add_f32_e32 v163, 1.0, v163
	v_add_f32_e32 v162, 1.0, v162
	v_rcp_f32_e32 v156, v156
	v_rcp_f32_e32 v157, v157
	v_rcp_f32_e32 v158, v158
	v_rcp_f32_e32 v159, v159
	v_rcp_f32_e32 v160, v160
	v_rcp_f32_e32 v161, v161
	v_rcp_f32_e32 v163, v163
	v_rcp_f32_e32 v162, v162
	v_mul_f32_e32 v153, v153, v156
	v_mul_f32_e32 v117, v117, v157
	v_mul_f32_e32 v125, v125, v158
	v_mul_f32_e32 v119, v119, v159
	v_mul_f32_e32 v127, v127, v160
	v_mul_f32_e32 v113, v113, v161
	v_mul_f32_e32 v115, v115, v163
	v_mul_f32_e32 v155, v155, v162
	v_mul_f32_e32 v152, v152, v153
	v_mul_f32_e32 v116, v116, v117
	v_mul_f32_e32 v117, v124, v125
	v_mul_f32_e32 v118, v118, v119
	v_mul_f32_e32 v119, v126, v127
	v_mul_f32_e32 v124, v112, v113
	v_mul_f32_e32 v115, v114, v115
	v_cvt_pk_bf16_f32 v112, v152, v116
	v_cvt_pk_bf16_f32 v113, v117, v118
	v_cvt_pk_bf16_f32 v114, v119, v124
	v_mul_f32_e32 v125, v154, v155
	v_cvt_pk_bf16_f32 v115, v125, v115
	global_store_dwordx4 v[122:123], v[112:115], off
	v_add_u32_e32 v117, 32, v151
	s_nop 0
	v_add_u32_e32 v114, 16, v151
	v_add_u32_e32 v112, s4, v114
	v_ashrrev_i32_e32 v113, 31, v112
	v_lshl_add_u64 v[112:113], v[112:113], 2, s[14:15]
	global_load_dword v115, v[112:113], off
	v_mov_b32_e32 v113, v100
	v_mov_b32_e32 v100, v109
	v_mov_b32_e32 v109, v102
	v_mov_b32_e32 v102, v111
	v_mov_b32_e32 v111, v96
	v_mov_b32_e32 v96, v105
	v_mov_b32_e32 v105, v98
	v_mov_b32_e32 v98, v107
	v_mov_b32_e32 v112, v108
	v_mov_b32_e32 v108, v110
	v_mov_b32_e32 v110, v104
	v_mov_b32_e32 v104, v106
	v_add_u32_e32 v106, s4, v117
	v_ashrrev_i32_e32 v107, 31, v106
	v_lshl_add_u64 v[106:107], v[106:107], 2, s[14:15]
	s_waitcnt vmcnt(0)
; __device__ __forceinline__ void st8(bf16_t* p, f32x4 a, f32x4 b) { u32x4 w; w.x = cvt_pk_bf16(a[0], a[1]); w.y = cvt_pk_bf16(a[2], a[3]); w.z = cvt_pk_bf16(b[0], b[1]); w.w = cvt_pk_bf16(b[2], b[3]); *(u32x4*)p = w; }
;     __device__ __forceinline__ void operator()(const f32x4 (&acc)[2][2][4][2], const Unit& u, int wr, int wc, int fr, int fq) const {
;     ...
;         for (int ai = 0; ai < 2; ++ai)
; #pragma unroll
;             for (int m = 0; m < 4; ++m) {
;                 const int rl = rl0 + ai * HALF + m * 16;
;                 const float s = rsqrtf(ssqX[u.pm * BM + rl] * (1.0f / 1024.0f) + EPS);
;                 f32x4 o[2];
; #pragma unroll
;                 for (int n = 0; n < 2; ++n) {
;                     const f32x4 g = acc[ai][0][m][n] * s, up = acc[ai][1][m][n] * s;
; #pragma unroll
;                     for (int j = 0; j < 4; ++j) { const float e = __builtin_amdgcn_exp2f(g[j] * -1.4426950408889634f); o[n][j] = g[j] * __builtin_amdgcn_rcpf(1.0f + e) * up[j]; }
;                 }
;                 st8(base + (size_t)rl * 2816 + pn * 128 + cw, o[0], o[1]);
;                 asm volatile("" ::: "memory");
	v_fmamk_f32 v115, v115, 0x3a800000, v150
	v_mul_f32_e32 v116, 0x4b800000, v115
	v_cmp_gt_f32_e32 vcc, s58, v115
	s_nop 1
	v_cndmask_b32_e32 v115, v115, v116, vcc
	v_rsq_f32_e32 v116, v115
	v_mad_i64_i32 v[114:115], s[30:31], v114, s59, v[120:121]
	v_mul_f32_e32 v118, 0x45800000, v116
	v_cndmask_b32_e32 v116, v116, v118, vcc
	v_pk_mul_f32 v[98:99], v[98:99], v[116:117] op_sel_hi:[1,0]
	v_pk_mul_f32 v[112:113], v[112:113], v[116:117] op_sel_hi:[1,0]
	v_pk_mul_f32 v[100:101], v[100:101], v[116:117] op_sel_hi:[1,0]
	v_pk_mul_f32 v[108:109], v[108:109], v[116:117] op_sel_hi:[1,0]
	v_pk_mul_f32 v[102:103], v[102:103], v[116:117] op_sel_hi:[1,0]
	v_pk_mul_f32 v[110:111], v[110:111], v[116:117] op_sel_hi:[1,0]
	v_pk_mul_f32 v[96:97], v[96:97], v[116:117] op_sel_hi:[1,0]
	v_pk_mul_f32 v[104:105], v[104:105], v[116:117] op_sel_hi:[1,0]
	v_mul_f32_e32 v126, 0xbfb8aa3b, v99
	v_mul_f32_e32 v116, 0xbfb8aa3b, v113
	v_mul_f32_e32 v118, 0xbfb8aa3b, v101
	v_mul_f32_e32 v119, 0xbfb8aa3b, v109
	v_mul_f32_e32 v122, 0xbfb8aa3b, v103
	v_mul_f32_e32 v123, 0xbfb8aa3b, v111
	v_mul_f32_e32 v124, 0xbfb8aa3b, v97
	v_mul_f32_e32 v125, 0xbfb8aa3b, v105
	v_exp_f32_e32 v126, v126
	v_exp_f32_e32 v116, v116
	v_exp_f32_e32 v118, v118
	v_exp_f32_e32 v119, v119
	v_exp_f32_e32 v122, v122
	v_exp_f32_e32 v123, v123
	v_exp_f32_e32 v124, v124
	v_exp_f32_e32 v125, v125
	v_add_f32_e32 v126, 1.0, v126
	v_add_f32_e32 v116, 1.0, v116
	v_add_f32_e32 v118, 1.0, v118
	v_add_f32_e32 v119, 1.0, v119
	v_add_f32_e32 v122, 1.0, v122
	v_add_f32_e32 v123, 1.0, v123
	v_add_f32_e32 v124, 1.0, v124
	v_add_f32_e32 v125, 1.0, v125
	v_rcp_f32_e32 v126, v126
	v_rcp_f32_e32 v116, v116
	v_rcp_f32_e32 v118, v118
	v_rcp_f32_e32 v119, v119
	v_rcp_f32_e32 v122, v122
	v_rcp_f32_e32 v123, v123
	v_rcp_f32_e32 v124, v124
	v_rcp_f32_e32 v125, v125
	v_mul_f32_e32 v99, v99, v126
	v_mul_f32_e32 v113, v113, v116
	v_mul_f32_e32 v101, v101, v118
	v_mul_f32_e32 v109, v109, v119
	v_mul_f32_e32 v103, v103, v122
	v_mul_f32_e32 v111, v111, v123
	v_mul_f32_e32 v97, v97, v124
	v_mul_f32_e32 v105, v105, v125
	v_mul_f32_e32 v99, v98, v99
	v_mul_f32_e32 v112, v112, v113
	v_mul_f32_e32 v100, v100, v101
	v_mul_f32_e32 v101, v108, v109
	v_mul_f32_e32 v102, v102, v103
	v_mul_f32_e32 v103, v110, v111
	v_mul_f32_e32 v108, v96, v97
	v_mul_f32_e32 v104, v104, v105
	v_cvt_pk_bf16_f32 v96, v112, v100
	v_cvt_pk_bf16_f32 v97, v101, v102
	v_cvt_pk_bf16_f32 v98, v103, v108
	v_cvt_pk_bf16_f32 v99, v104, v99
	global_store_dwordx4 v[114:115], v[96:99], off
	global_load_dword v98, v[106:107], off
	v_add_u32_e32 v101, 48, v151
	v_mov_b32_e32 v97, v84
	v_mov_b32_e32 v84, v93
	v_mov_b32_e32 v93, v86
	v_mov_b32_e32 v86, v95
	v_mov_b32_e32 v95, v80
	v_mov_b32_e32 v80, v89
	v_mov_b32_e32 v89, v82
	v_mov_b32_e32 v82, v91
	v_mov_b32_e32 v96, v92
	v_mov_b32_e32 v92, v94
	v_mov_b32_e32 v94, v88
	v_mov_b32_e32 v88, v90
	v_add_u32_e32 v90, s4, v101
	v_ashrrev_i32_e32 v91, 31, v90
	v_lshl_add_u64 v[90:91], v[90:91], 2, s[14:15]
	s_waitcnt vmcnt(0)
	v_fmamk_f32 v98, v98, 0x3a800000, v150
	v_mul_f32_e32 v99, 0x4b800000, v98
	v_cmp_gt_f32_e32 vcc, s58, v98
	s_nop 1
	v_cndmask_b32_e32 v98, v98, v99, vcc
	v_rsq_f32_e32 v100, v98
	v_mad_i64_i32 v[98:99], s[30:31], v117, s59, v[120:121]
	v_mul_f32_e32 v102, 0x45800000, v100
	v_cndmask_b32_e32 v100, v100, v102, vcc
	v_pk_mul_f32 v[82:83], v[82:83], v[100:101] op_sel_hi:[1,0]
	v_pk_mul_f32 v[96:97], v[96:97], v[100:101] op_sel_hi:[1,0]
	v_pk_mul_f32 v[84:85], v[84:85], v[100:101] op_sel_hi:[1,0]
	v_pk_mul_f32 v[92:93], v[92:93], v[100:101] op_sel_hi:[1,0]
	v_pk_mul_f32 v[86:87], v[86:87], v[100:101] op_sel_hi:[1,0]
	v_pk_mul_f32 v[94:95], v[94:95], v[100:101] op_sel_hi:[1,0]
	v_pk_mul_f32 v[80:81], v[80:81], v[100:101] op_sel_hi:[1,0]
	v_pk_mul_f32 v[88:89], v[88:89], v[100:101] op_sel_hi:[1,0]
	v_mul_f32_e32 v108, 0xbfb8aa3b, v83
	v_mul_f32_e32 v100, 0xbfb8aa3b, v97
	v_mul_f32_e32 v102, 0xbfb8aa3b, v85
	v_mul_f32_e32 v103, 0xbfb8aa3b, v93
	v_mul_f32_e32 v104, 0xbfb8aa3b, v87
	v_mul_f32_e32 v105, 0xbfb8aa3b, v95
	v_mul_f32_e32 v106, 0xbfb8aa3b, v81
	v_mul_f32_e32 v107, 0xbfb8aa3b, v89
	v_exp_f32_e32 v108, v108
	v_exp_f32_e32 v100, v100
	v_exp_f32_e32 v102, v102
	v_exp_f32_e32 v103, v103
	v_exp_f32_e32 v104, v104
	v_exp_f32_e32 v105, v105
	v_exp_f32_e32 v106, v106
	v_exp_f32_e32 v107, v107
	v_add_f32_e32 v108, 1.0, v108
	v_add_f32_e32 v100, 1.0, v100
	v_add_f32_e32 v102, 1.0, v102
	v_add_f32_e32 v103, 1.0, v103
	v_add_f32_e32 v104, 1.0, v104
	v_add_f32_e32 v105, 1.0, v105
	v_add_f32_e32 v106, 1.0, v106
	v_add_f32_e32 v107, 1.0, v107
	v_rcp_f32_e32 v108, v108
	v_rcp_f32_e32 v100, v100
	v_rcp_f32_e32 v102, v102
	v_rcp_f32_e32 v103, v103
	v_rcp_f32_e32 v104, v104
	v_rcp_f32_e32 v105, v105
	v_rcp_f32_e32 v106, v106
	v_rcp_f32_e32 v107, v107
	v_mul_f32_e32 v83, v83, v108
	v_mul_f32_e32 v97, v97, v100
	v_mul_f32_e32 v85, v85, v102
	v_mul_f32_e32 v93, v93, v103
	v_mul_f32_e32 v87, v87, v104
	v_mul_f32_e32 v95, v95, v105
	v_mul_f32_e32 v81, v81, v106
	v_mul_f32_e32 v89, v89, v107
	v_mul_f32_e32 v83, v82, v83
	v_mul_f32_e32 v96, v96, v97
	v_mul_f32_e32 v84, v84, v85
	v_mul_f32_e32 v85, v92, v93
	v_mul_f32_e32 v86, v86, v87
	v_mul_f32_e32 v87, v94, v95
	v_mul_f32_e32 v92, v80, v81
	v_mul_f32_e32 v88, v88, v89
	v_cvt_pk_bf16_f32 v80, v96, v84
	v_cvt_pk_bf16_f32 v81, v85, v86
	v_cvt_pk_bf16_f32 v82, v87, v92
	v_cvt_pk_bf16_f32 v83, v88, v83
	global_store_dwordx4 v[98:99], v[80:83], off
	global_load_dword v82, v[90:91], off
	v_add_u32_e32 v85, 0x80, v151
	v_mov_b32_e32 v81, v68
	v_mov_b32_e32 v68, v77
	v_mov_b32_e32 v77, v70
	v_mov_b32_e32 v70, v79
	v_mov_b32_e32 v79, v64
	v_mov_b32_e32 v64, v73
	v_mov_b32_e32 v73, v66
	v_mov_b32_e32 v66, v75
	v_mov_b32_e32 v80, v76
	v_mov_b32_e32 v76, v78
	v_mov_b32_e32 v78, v72
	v_mov_b32_e32 v72, v74
	v_add_u32_e32 v74, s4, v85
	v_ashrrev_i32_e32 v75, 31, v74
	v_lshl_add_u64 v[74:75], v[74:75], 2, s[14:15]
	s_waitcnt vmcnt(0)
; __device__ __forceinline__ void st8(bf16_t* p, f32x4 a, f32x4 b) { u32x4 w; w.x = cvt_pk_bf16(a[0], a[1]); w.y = cvt_pk_bf16(a[2], a[3]); w.z = cvt_pk_bf16(b[0], b[1]); w.w = cvt_pk_bf16(b[2], b[3]); *(u32x4*)p = w; }
;     __device__ __forceinline__ void operator()(const f32x4 (&acc)[2][2][4][2], const Unit& u, int wr, int wc, int fr, int fq) const {
;     ...
;         for (int ai = 0; ai < 2; ++ai)
; #pragma unroll
;             for (int m = 0; m < 4; ++m) {
;                 const int rl = rl0 + ai * HALF + m * 16;
;                 const float s = rsqrtf(ssqX[u.pm * BM + rl] * (1.0f / 1024.0f) + EPS);
;                 f32x4 o[2];
; #pragma unroll
;                 for (int n = 0; n < 2; ++n) {
;                     const f32x4 g = acc[ai][0][m][n] * s, up = acc[ai][1][m][n] * s;
; #pragma unroll
;                     for (int j = 0; j < 4; ++j) { const float e = __builtin_amdgcn_exp2f(g[j] * -1.4426950408889634f); o[n][j] = g[j] * __builtin_amdgcn_rcpf(1.0f + e) * up[j]; }
;                 }
;                 st8(base + (size_t)rl * 2816 + pn * 128 + cw, o[0], o[1]);
;                 asm volatile("" ::: "memory");
	v_fmamk_f32 v82, v82, 0x3a800000, v150
	v_mul_f32_e32 v83, 0x4b800000, v82
	v_cmp_gt_f32_e32 vcc, s58, v82
	s_nop 1
	v_cndmask_b32_e32 v82, v82, v83, vcc
	v_rsq_f32_e32 v84, v82
	v_mad_i64_i32 v[82:83], s[30:31], v101, s59, v[120:121]
	v_mul_f32_e32 v86, 0x45800000, v84
	v_cndmask_b32_e32 v84, v84, v86, vcc
	v_pk_mul_f32 v[66:67], v[66:67], v[84:85] op_sel_hi:[1,0]
	v_pk_mul_f32 v[80:81], v[80:81], v[84:85] op_sel_hi:[1,0]
	v_pk_mul_f32 v[68:69], v[68:69], v[84:85] op_sel_hi:[1,0]
	v_pk_mul_f32 v[76:77], v[76:77], v[84:85] op_sel_hi:[1,0]
	v_pk_mul_f32 v[70:71], v[70:71], v[84:85] op_sel_hi:[1,0]
	v_pk_mul_f32 v[78:79], v[78:79], v[84:85] op_sel_hi:[1,0]
	v_pk_mul_f32 v[64:65], v[64:65], v[84:85] op_sel_hi:[1,0]
	v_pk_mul_f32 v[72:73], v[72:73], v[84:85] op_sel_hi:[1,0]
	v_mul_f32_e32 v92, 0xbfb8aa3b, v67
	v_mul_f32_e32 v84, 0xbfb8aa3b, v81
	v_mul_f32_e32 v86, 0xbfb8aa3b, v69
	v_mul_f32_e32 v87, 0xbfb8aa3b, v77
	v_mul_f32_e32 v88, 0xbfb8aa3b, v71
	v_mul_f32_e32 v89, 0xbfb8aa3b, v79
	v_mul_f32_e32 v90, 0xbfb8aa3b, v65
	v_mul_f32_e32 v91, 0xbfb8aa3b, v73
	v_exp_f32_e32 v92, v92
	v_exp_f32_e32 v84, v84
	v_exp_f32_e32 v86, v86
	v_exp_f32_e32 v87, v87
	v_exp_f32_e32 v88, v88
	v_exp_f32_e32 v89, v89
	v_exp_f32_e32 v90, v90
	v_exp_f32_e32 v91, v91
	v_add_f32_e32 v92, 1.0, v92
	v_add_f32_e32 v84, 1.0, v84
	v_add_f32_e32 v86, 1.0, v86
	v_add_f32_e32 v87, 1.0, v87
	v_add_f32_e32 v88, 1.0, v88
	v_add_f32_e32 v89, 1.0, v89
	v_add_f32_e32 v90, 1.0, v90
	v_add_f32_e32 v91, 1.0, v91
	v_rcp_f32_e32 v92, v92
	v_rcp_f32_e32 v84, v84
	v_rcp_f32_e32 v86, v86
	v_rcp_f32_e32 v87, v87
	v_rcp_f32_e32 v88, v88
	v_rcp_f32_e32 v89, v89
	v_rcp_f32_e32 v90, v90
	v_rcp_f32_e32 v91, v91
	v_mul_f32_e32 v67, v67, v92
	v_mul_f32_e32 v81, v81, v84
	v_mul_f32_e32 v69, v69, v86
	v_mul_f32_e32 v77, v77, v87
	v_mul_f32_e32 v71, v71, v88
	v_mul_f32_e32 v79, v79, v89
	v_mul_f32_e32 v65, v65, v90
	v_mul_f32_e32 v73, v73, v91
	v_mul_f32_e32 v67, v66, v67
	v_mul_f32_e32 v80, v80, v81
	v_mul_f32_e32 v68, v68, v69
	v_mul_f32_e32 v69, v76, v77
	v_mul_f32_e32 v70, v70, v71
	v_mul_f32_e32 v71, v78, v79
	v_mul_f32_e32 v76, v64, v65
	v_mul_f32_e32 v72, v72, v73
	v_cvt_pk_bf16_f32 v64, v80, v68
	v_cvt_pk_bf16_f32 v65, v69, v70
	v_cvt_pk_bf16_f32 v66, v71, v76
	v_cvt_pk_bf16_f32 v67, v72, v67
	global_store_dwordx4 v[82:83], v[64:67], off
	global_load_dword v66, v[74:75], off
	v_add_u32_e32 v69, 0x90, v151
	v_mov_b32_e32 v65, v52
	v_mov_b32_e32 v52, v61
	v_mov_b32_e32 v61, v54
	v_mov_b32_e32 v54, v63
	v_mov_b32_e32 v63, v48
	v_mov_b32_e32 v48, v57
	v_mov_b32_e32 v57, v50
	v_mov_b32_e32 v50, v59
	v_mov_b32_e32 v64, v60
	v_mov_b32_e32 v60, v62
	v_mov_b32_e32 v62, v56
	v_mov_b32_e32 v56, v58
	v_add_u32_e32 v58, s4, v69
	v_ashrrev_i32_e32 v59, 31, v58
	v_lshl_add_u64 v[58:59], v[58:59], 2, s[14:15]
	s_waitcnt vmcnt(0)
	v_fmamk_f32 v66, v66, 0x3a800000, v150
	v_mul_f32_e32 v67, 0x4b800000, v66
	v_cmp_gt_f32_e32 vcc, s58, v66
	s_nop 1
	v_cndmask_b32_e32 v66, v66, v67, vcc
	v_rsq_f32_e32 v68, v66
	v_mad_i64_i32 v[66:67], s[30:31], v85, s59, v[120:121]
	v_mul_f32_e32 v70, 0x45800000, v68
	v_cndmask_b32_e32 v68, v68, v70, vcc
	v_pk_mul_f32 v[50:51], v[50:51], v[68:69] op_sel_hi:[1,0]
	v_pk_mul_f32 v[64:65], v[64:65], v[68:69] op_sel_hi:[1,0]
	v_pk_mul_f32 v[52:53], v[52:53], v[68:69] op_sel_hi:[1,0]
	v_pk_mul_f32 v[60:61], v[60:61], v[68:69] op_sel_hi:[1,0]
	v_pk_mul_f32 v[54:55], v[54:55], v[68:69] op_sel_hi:[1,0]
	v_pk_mul_f32 v[62:63], v[62:63], v[68:69] op_sel_hi:[1,0]
	v_pk_mul_f32 v[48:49], v[48:49], v[68:69] op_sel_hi:[1,0]
	v_pk_mul_f32 v[56:57], v[56:57], v[68:69] op_sel_hi:[1,0]
	v_mul_f32_e32 v76, 0xbfb8aa3b, v51
	v_mul_f32_e32 v68, 0xbfb8aa3b, v65
	v_mul_f32_e32 v70, 0xbfb8aa3b, v53
	v_mul_f32_e32 v71, 0xbfb8aa3b, v61
	v_mul_f32_e32 v72, 0xbfb8aa3b, v55
	v_mul_f32_e32 v73, 0xbfb8aa3b, v63
	v_mul_f32_e32 v74, 0xbfb8aa3b, v49
	v_mul_f32_e32 v75, 0xbfb8aa3b, v57
	v_exp_f32_e32 v76, v76
	v_exp_f32_e32 v68, v68
	v_exp_f32_e32 v70, v70
	v_exp_f32_e32 v71, v71
	v_exp_f32_e32 v72, v72
	v_exp_f32_e32 v73, v73
	v_exp_f32_e32 v74, v74
	v_exp_f32_e32 v75, v75
	v_add_f32_e32 v76, 1.0, v76
	v_add_f32_e32 v68, 1.0, v68
	v_add_f32_e32 v70, 1.0, v70
	v_add_f32_e32 v71, 1.0, v71
	v_add_f32_e32 v72, 1.0, v72
	v_add_f32_e32 v73, 1.0, v73
	v_add_f32_e32 v74, 1.0, v74
	v_add_f32_e32 v75, 1.0, v75
	v_rcp_f32_e32 v76, v76
	v_rcp_f32_e32 v68, v68
	v_rcp_f32_e32 v70, v70
	v_rcp_f32_e32 v71, v71
	v_rcp_f32_e32 v72, v72
	v_rcp_f32_e32 v73, v73
	v_rcp_f32_e32 v74, v74
	v_rcp_f32_e32 v75, v75
	v_mul_f32_e32 v51, v51, v76
	v_mul_f32_e32 v65, v65, v68
	v_mul_f32_e32 v53, v53, v70
	v_mul_f32_e32 v61, v61, v71
	v_mul_f32_e32 v55, v55, v72
	v_mul_f32_e32 v63, v63, v73
	v_mul_f32_e32 v49, v49, v74
	v_mul_f32_e32 v57, v57, v75
	v_mul_f32_e32 v51, v50, v51
	v_mul_f32_e32 v64, v64, v65
	v_mul_f32_e32 v52, v52, v53
	v_mul_f32_e32 v53, v60, v61
	v_mul_f32_e32 v54, v54, v55
	v_mul_f32_e32 v55, v62, v63
	v_mul_f32_e32 v60, v48, v49
	v_mul_f32_e32 v56, v56, v57
	v_cvt_pk_bf16_f32 v48, v64, v52
	v_cvt_pk_bf16_f32 v49, v53, v54
	v_cvt_pk_bf16_f32 v50, v55, v60
	v_cvt_pk_bf16_f32 v51, v56, v51
	global_store_dwordx4 v[66:67], v[48:51], off
	global_load_dword v50, v[58:59], off
	v_add_u32_e32 v53, 0xa0, v151
	v_mov_b32_e32 v49, v36
	v_mov_b32_e32 v36, v45
	v_mov_b32_e32 v45, v38
	v_mov_b32_e32 v38, v47
	v_mov_b32_e32 v47, v32
	v_mov_b32_e32 v32, v41
	v_mov_b32_e32 v41, v34
	v_mov_b32_e32 v34, v43
	v_mov_b32_e32 v48, v44
	v_mov_b32_e32 v44, v46
	v_mov_b32_e32 v46, v40
	v_mov_b32_e32 v40, v42
	v_add_u32_e32 v42, s4, v53
	v_ashrrev_i32_e32 v43, 31, v42
	v_lshl_add_u64 v[42:43], v[42:43], 2, s[14:15]
	s_waitcnt vmcnt(0)
; __device__ __forceinline__ void st8(bf16_t* p, f32x4 a, f32x4 b) { u32x4 w; w.x = cvt_pk_bf16(a[0], a[1]); w.y = cvt_pk_bf16(a[2], a[3]); w.z = cvt_pk_bf16(b[0], b[1]); w.w = cvt_pk_bf16(b[2], b[3]); *(u32x4*)p = w; }
;     __device__ __forceinline__ void operator()(const f32x4 (&acc)[2][2][4][2], const Unit& u, int wr, int wc, int fr, int fq) const {
;     ...
;         for (int ai = 0; ai < 2; ++ai)
; #pragma unroll
;             for (int m = 0; m < 4; ++m) {
;                 const int rl = rl0 + ai * HALF + m * 16;
;                 const float s = rsqrtf(ssqX[u.pm * BM + rl] * (1.0f / 1024.0f) + EPS);
;                 f32x4 o[2];
; #pragma unroll
;                 for (int n = 0; n < 2; ++n) {
;                     const f32x4 g = acc[ai][0][m][n] * s, up = acc[ai][1][m][n] * s;
; #pragma unroll
;                     for (int j = 0; j < 4; ++j) { const float e = __builtin_amdgcn_exp2f(g[j] * -1.4426950408889634f); o[n][j] = g[j] * __builtin_amdgcn_rcpf(1.0f + e) * up[j]; }
;                 }
;                 st8(base + (size_t)rl * 2816 + pn * 128 + cw, o[0], o[1]);
;                 asm volatile("" ::: "memory");
	v_fmamk_f32 v50, v50, 0x3a800000, v150
	v_mul_f32_e32 v51, 0x4b800000, v50
	v_cmp_gt_f32_e32 vcc, s58, v50
	s_nop 1
	v_cndmask_b32_e32 v50, v50, v51, vcc
	v_rsq_f32_e32 v52, v50
	v_mad_i64_i32 v[50:51], s[30:31], v69, s59, v[120:121]
	v_mul_f32_e32 v54, 0x45800000, v52
	v_cndmask_b32_e32 v52, v52, v54, vcc
	v_pk_mul_f32 v[34:35], v[34:35], v[52:53] op_sel_hi:[1,0]
	v_pk_mul_f32 v[48:49], v[48:49], v[52:53] op_sel_hi:[1,0]
	v_pk_mul_f32 v[36:37], v[36:37], v[52:53] op_sel_hi:[1,0]
	v_pk_mul_f32 v[44:45], v[44:45], v[52:53] op_sel_hi:[1,0]
	v_pk_mul_f32 v[38:39], v[38:39], v[52:53] op_sel_hi:[1,0]
	v_pk_mul_f32 v[46:47], v[46:47], v[52:53] op_sel_hi:[1,0]
	v_pk_mul_f32 v[32:33], v[32:33], v[52:53] op_sel_hi:[1,0]
	v_pk_mul_f32 v[40:41], v[40:41], v[52:53] op_sel_hi:[1,0]
	v_mul_f32_e32 v60, 0xbfb8aa3b, v35
	v_mul_f32_e32 v52, 0xbfb8aa3b, v49
	v_mul_f32_e32 v54, 0xbfb8aa3b, v37
	v_mul_f32_e32 v55, 0xbfb8aa3b, v45
	v_mul_f32_e32 v56, 0xbfb8aa3b, v39
	v_mul_f32_e32 v57, 0xbfb8aa3b, v47
	v_mul_f32_e32 v58, 0xbfb8aa3b, v33
	v_mul_f32_e32 v59, 0xbfb8aa3b, v41
	v_exp_f32_e32 v60, v60
	v_exp_f32_e32 v52, v52
	v_exp_f32_e32 v54, v54
	v_exp_f32_e32 v55, v55
	v_exp_f32_e32 v56, v56
	v_exp_f32_e32 v57, v57
	v_exp_f32_e32 v58, v58
	v_exp_f32_e32 v59, v59
	v_add_f32_e32 v60, 1.0, v60
	v_add_f32_e32 v52, 1.0, v52
	v_add_f32_e32 v54, 1.0, v54
	v_add_f32_e32 v55, 1.0, v55
	v_add_f32_e32 v56, 1.0, v56
	v_add_f32_e32 v57, 1.0, v57
	v_add_f32_e32 v58, 1.0, v58
	v_add_f32_e32 v59, 1.0, v59
	v_rcp_f32_e32 v60, v60
	v_rcp_f32_e32 v52, v52
	v_rcp_f32_e32 v54, v54
	v_rcp_f32_e32 v55, v55
	v_rcp_f32_e32 v56, v56
	v_rcp_f32_e32 v57, v57
	v_rcp_f32_e32 v58, v58
	v_rcp_f32_e32 v59, v59
	v_mul_f32_e32 v35, v35, v60
	v_mul_f32_e32 v49, v49, v52
	v_mul_f32_e32 v37, v37, v54
	v_mul_f32_e32 v45, v45, v55
	v_mul_f32_e32 v39, v39, v56
	v_mul_f32_e32 v47, v47, v57
	v_mul_f32_e32 v33, v33, v58
	v_mul_f32_e32 v41, v41, v59
	v_mul_f32_e32 v35, v34, v35
	v_mul_f32_e32 v48, v48, v49
	v_mul_f32_e32 v36, v36, v37
	v_mul_f32_e32 v37, v44, v45
	v_mul_f32_e32 v38, v38, v39
	v_mul_f32_e32 v39, v46, v47
	v_mul_f32_e32 v44, v32, v33
	v_mul_f32_e32 v40, v40, v41
	v_cvt_pk_bf16_f32 v32, v48, v36
	v_cvt_pk_bf16_f32 v33, v37, v38
	v_cvt_pk_bf16_f32 v34, v39, v44
	v_cvt_pk_bf16_f32 v35, v40, v35
	global_store_dwordx4 v[50:51], v[32:35], off
	global_load_dword v34, v[42:43], off
	v_add_u32_e32 v37, 0xb0, v151
	v_mov_b32_e32 v33, v20
	v_mov_b32_e32 v20, v29
	v_mov_b32_e32 v29, v22
	v_mov_b32_e32 v22, v31
	v_mov_b32_e32 v31, v16
	v_mov_b32_e32 v16, v25
	v_mov_b32_e32 v25, v18
	v_mov_b32_e32 v18, v27
	v_mov_b32_e32 v32, v28
	v_mov_b32_e32 v28, v30
	v_mov_b32_e32 v30, v24
	v_mov_b32_e32 v24, v26
	v_add_u32_e32 v26, s4, v37
	v_ashrrev_i32_e32 v27, 31, v26
	v_lshl_add_u64 v[26:27], v[26:27], 2, s[14:15]
	s_waitcnt vmcnt(0)
; __device__ __forceinline__ void st8(bf16_t* p, f32x4 a, f32x4 b) { u32x4 w; w.x = cvt_pk_bf16(a[0], a[1]); w.y = cvt_pk_bf16(a[2], a[3]); w.z = cvt_pk_bf16(b[0], b[1]); w.w = cvt_pk_bf16(b[2], b[3]); *(u32x4*)p = w; }
;     __device__ __forceinline__ void operator()(const f32x4 (&acc)[2][2][4][2], const Unit& u, int wr, int wc, int fr, int fq) const {
;     ...
;         for (int ai = 0; ai < 2; ++ai)
; #pragma unroll
;             for (int m = 0; m < 4; ++m) {
;                 const int rl = rl0 + ai * HALF + m * 16;
;                 const float s = rsqrtf(ssqX[u.pm * BM + rl] * (1.0f / 1024.0f) + EPS);
;                 f32x4 o[2];
; #pragma unroll
;                 for (int n = 0; n < 2; ++n) {
;                     const f32x4 g = acc[ai][0][m][n] * s, up = acc[ai][1][m][n] * s;
; #pragma unroll
;                     for (int j = 0; j < 4; ++j) { const float e = __builtin_amdgcn_exp2f(g[j] * -1.4426950408889634f); o[n][j] = g[j] * __builtin_amdgcn_rcpf(1.0f + e) * up[j]; }
;                 }
;                 st8(base + (size_t)rl * 2816 + pn * 128 + cw, o[0], o[1]);
;                 asm volatile("" ::: "memory");
;             }
	v_fmamk_f32 v34, v34, 0x3a800000, v150
	v_mul_f32_e32 v35, 0x4b800000, v34
	v_cmp_gt_f32_e32 vcc, s58, v34
	s_nop 1
	v_cndmask_b32_e32 v34, v34, v35, vcc
	v_rsq_f32_e32 v36, v34
	v_mad_i64_i32 v[34:35], s[4:5], v53, s59, v[120:121]
	v_mul_f32_e32 v38, 0x45800000, v36
	v_cndmask_b32_e32 v36, v36, v38, vcc
	v_pk_mul_f32 v[18:19], v[18:19], v[36:37] op_sel_hi:[1,0]
	v_pk_mul_f32 v[32:33], v[32:33], v[36:37] op_sel_hi:[1,0]
	v_pk_mul_f32 v[20:21], v[20:21], v[36:37] op_sel_hi:[1,0]
	v_pk_mul_f32 v[28:29], v[28:29], v[36:37] op_sel_hi:[1,0]
	v_pk_mul_f32 v[22:23], v[22:23], v[36:37] op_sel_hi:[1,0]
	v_pk_mul_f32 v[30:31], v[30:31], v[36:37] op_sel_hi:[1,0]
	v_pk_mul_f32 v[16:17], v[16:17], v[36:37] op_sel_hi:[1,0]
	v_pk_mul_f32 v[24:25], v[24:25], v[36:37] op_sel_hi:[1,0]
	v_mul_f32_e32 v44, 0xbfb8aa3b, v19
	v_mul_f32_e32 v36, 0xbfb8aa3b, v33
	v_mul_f32_e32 v38, 0xbfb8aa3b, v21
	v_mul_f32_e32 v39, 0xbfb8aa3b, v29
	v_mul_f32_e32 v40, 0xbfb8aa3b, v23
	v_mul_f32_e32 v41, 0xbfb8aa3b, v31
	v_mul_f32_e32 v42, 0xbfb8aa3b, v17
	v_mul_f32_e32 v43, 0xbfb8aa3b, v25
	v_exp_f32_e32 v44, v44
	v_exp_f32_e32 v36, v36
	v_exp_f32_e32 v38, v38
	v_exp_f32_e32 v39, v39
	v_exp_f32_e32 v40, v40
	v_exp_f32_e32 v41, v41
	v_exp_f32_e32 v42, v42
	v_exp_f32_e32 v43, v43
	v_add_f32_e32 v44, 1.0, v44
	v_add_f32_e32 v36, 1.0, v36
	v_add_f32_e32 v38, 1.0, v38
	v_add_f32_e32 v39, 1.0, v39
	v_add_f32_e32 v40, 1.0, v40
	v_add_f32_e32 v41, 1.0, v41
	v_add_f32_e32 v42, 1.0, v42
	v_add_f32_e32 v43, 1.0, v43
	v_rcp_f32_e32 v44, v44
	v_rcp_f32_e32 v36, v36
	v_rcp_f32_e32 v38, v38
	v_rcp_f32_e32 v39, v39
	v_rcp_f32_e32 v40, v40
	v_rcp_f32_e32 v41, v41
	v_rcp_f32_e32 v42, v42
	v_rcp_f32_e32 v43, v43
	v_mul_f32_e32 v19, v19, v44
	v_mul_f32_e32 v33, v33, v36
	v_mul_f32_e32 v21, v21, v38
	v_mul_f32_e32 v29, v29, v39
	v_mul_f32_e32 v23, v23, v40
	v_mul_f32_e32 v31, v31, v41
	v_mul_f32_e32 v17, v17, v42
	v_mul_f32_e32 v25, v25, v43
	v_mul_f32_e32 v19, v18, v19
	v_mul_f32_e32 v32, v32, v33
	v_mul_f32_e32 v20, v20, v21
	v_mul_f32_e32 v21, v28, v29
	v_mul_f32_e32 v22, v22, v23
	v_mul_f32_e32 v23, v30, v31
	v_mul_f32_e32 v28, v16, v17
	v_mul_f32_e32 v24, v24, v25
	v_cvt_pk_bf16_f32 v16, v32, v20
	v_cvt_pk_bf16_f32 v17, v21, v22
	v_cvt_pk_bf16_f32 v18, v23, v28
	v_cvt_pk_bf16_f32 v19, v24, v19
	global_store_dwordx4 v[34:35], v[16:19], off
	global_load_dword v18, v[26:27], off
	s_nop 0
	v_mov_b32_e32 v17, v4
	v_mov_b32_e32 v4, v13
	v_mov_b32_e32 v13, v6
	v_mov_b32_e32 v6, v15
	v_mov_b32_e32 v15, v0
	v_mov_b32_e32 v0, v9
	v_mov_b32_e32 v9, v2
	v_mov_b32_e32 v16, v12
	v_mov_b32_e32 v12, v14
	v_mov_b32_e32 v14, v8
	v_mov_b32_e32 v8, v10
	s_waitcnt vmcnt(0)
	v_fmamk_f32 v2, v18, 0x3a800000, v150
	v_mul_f32_e32 v10, 0x4b800000, v2
	v_cmp_gt_f32_e32 vcc, s58, v2
	s_nop 1
	v_cndmask_b32_e32 v2, v2, v10, vcc
	v_rsq_f32_e32 v18, v2
	v_mov_b32_e32 v2, v11
	v_mad_i64_i32 v[10:11], s[4:5], v37, s59, v[120:121]
	v_mul_f32_e32 v19, 0x45800000, v18
	v_cndmask_b32_e32 v18, v18, v19, vcc
	v_pk_mul_f32 v[2:3], v[2:3], v[18:19] op_sel_hi:[1,0]
	v_pk_mul_f32 v[16:17], v[16:17], v[18:19] op_sel_hi:[1,0]
	v_pk_mul_f32 v[4:5], v[4:5], v[18:19] op_sel_hi:[1,0]
	v_pk_mul_f32 v[12:13], v[12:13], v[18:19] op_sel_hi:[1,0]
	v_pk_mul_f32 v[6:7], v[6:7], v[18:19] op_sel_hi:[1,0]
	v_pk_mul_f32 v[14:15], v[14:15], v[18:19] op_sel_hi:[1,0]
	v_pk_mul_f32 v[0:1], v[0:1], v[18:19] op_sel_hi:[1,0]
	v_pk_mul_f32 v[8:9], v[8:9], v[18:19] op_sel_hi:[1,0]
	v_mul_f32_e32 v25, 0xbfb8aa3b, v3
	v_mul_f32_e32 v18, 0xbfb8aa3b, v17
	v_mul_f32_e32 v19, 0xbfb8aa3b, v5
	v_mul_f32_e32 v20, 0xbfb8aa3b, v13
	v_mul_f32_e32 v21, 0xbfb8aa3b, v7
	v_mul_f32_e32 v22, 0xbfb8aa3b, v15
	v_mul_f32_e32 v23, 0xbfb8aa3b, v1
	v_mul_f32_e32 v24, 0xbfb8aa3b, v9
	v_exp_f32_e32 v25, v25
	v_exp_f32_e32 v18, v18
	v_exp_f32_e32 v19, v19
	v_exp_f32_e32 v20, v20
	v_exp_f32_e32 v21, v21
	v_exp_f32_e32 v22, v22
	v_exp_f32_e32 v23, v23
	v_exp_f32_e32 v24, v24
	v_add_f32_e32 v25, 1.0, v25
	v_add_f32_e32 v18, 1.0, v18
	v_add_f32_e32 v19, 1.0, v19
	v_add_f32_e32 v20, 1.0, v20
	v_add_f32_e32 v21, 1.0, v21
	v_add_f32_e32 v22, 1.0, v22
	v_add_f32_e32 v23, 1.0, v23
	v_add_f32_e32 v24, 1.0, v24
	v_rcp_f32_e32 v25, v25
	v_rcp_f32_e32 v18, v18
	v_rcp_f32_e32 v19, v19
	v_rcp_f32_e32 v20, v20
	v_rcp_f32_e32 v21, v21
	v_rcp_f32_e32 v22, v22
	v_rcp_f32_e32 v23, v23
	v_rcp_f32_e32 v24, v24
	v_mul_f32_e32 v3, v3, v25
	v_mul_f32_e32 v17, v17, v18
	v_mul_f32_e32 v5, v5, v19
	v_mul_f32_e32 v13, v13, v20
	v_mul_f32_e32 v7, v7, v21
	v_mul_f32_e32 v15, v15, v22
	v_mul_f32_e32 v1, v1, v23
	v_mul_f32_e32 v9, v9, v24
	v_mul_f32_e32 v3, v2, v3
	v_mul_f32_e32 v16, v16, v17
	v_mul_f32_e32 v4, v4, v5
	v_mul_f32_e32 v5, v12, v13
	v_mul_f32_e32 v6, v6, v7
	v_mul_f32_e32 v7, v14, v15
	v_mul_f32_e32 v12, v0, v1
	v_mul_f32_e32 v8, v8, v9
	v_cvt_pk_bf16_f32 v0, v16, v4
	v_cvt_pk_bf16_f32 v1, v5, v6
	v_cvt_pk_bf16_f32 v2, v7, v12
	v_cvt_pk_bf16_f32 v3, v8, v3
	global_store_dwordx4 v[10:11], v[0:3], off
	s_and_b64 vcc, exec, s[2:3]
	s_mov_b64 s[2:3], -1
	s_cbranch_vccnz .LBB0_1601
	s_andn2_b64 vcc, exec, s[12:13]
	s_cbranch_vccnz .LBB0_1600
	s_barrier
	s_branch .LBB0_1600

;     __host__ __device__ bool next(int i, Unit& u) const {
;         const long L = (long)i * G + c; if (L >= nwg) return false;
;         int wgid = (int)L; { const int q = nwg / NXCD, r = nwg % NXCD, xcd = wgid % NXCD, off = wgid / NXCD; wgid = (xcd < r ? xcd * (q + 1) : r * (q + 1) + (xcd - r) * q) + off; }
;         const int nig = WGM * nN, gid = wgid / nig, fm = gid * WGM, gsz = (nM - fm) < WGM ? (nM - fm) : WGM;
;         u.pm = fm + ((wgid % nig) % gsz); u.pn = (wgid % nig) / gsz; return true;
; template <class Epi, class Sched, bool ALIGN_EPI = false, bool SP2 = false>
; __device__ __forceinline__ void gemm_phase(PG8_LAS unsigned char* lds, const Gemm g, const Sched& S, const Epi& E) {
;     ...
;     const int wid = __builtin_amdgcn_readfirstlane(tid >> 6), lane = tid & 63, wr = wid >> 2, wc = wid & 3, fr = lane & 15, fq = lane >> 4;
;     int K = g.K; asm volatile("" : "+s"(K));
;     const int nt = K / BK;
;     unsigned voffA[2], voffB[2];
.LBB0_1664:
	v_mov_b32_e32 v251, 0
	s_cmp_lt_i32 s94, 16
	s_cselect_b64 s[4:5], -1, 0
	s_and_b64 s[0:1], s[4:5], s[2:3]
	s_andn2_b64 vcc, exec, s[0:1]
	s_cbranch_vccnz .LBB0_1707
.Lre_p7l1:
	v_readfirstlane_b32 s0, v183
	s_mov_b64 s[6:7], s[90:91]
	s_mov_b64 s[2:3], s[92:93]
	s_lshr_b32 s0, s0, 6
	v_mov_b32_e32 v0, v182
	s_mov_b32 s33, s96
	s_mov_b32 s36, s70
	v_readfirstlane_b32 vcc_lo, v251
	s_cmp_eq_u32 vcc_lo, 0
	s_cbranch_scc1 .Lm0_p7l1
	s_addk_i32 s36, 0x3f8
	s_mov_b32 s33, 0x10000
.Lm0_p7l1:
	v_mov_b32_e32 v12, v183
	s_cmpk_lt_i32 s36, 0x400
	s_movk_i32 s0, 0xb00
	v_readfirstlane_b32 s22, v12
	s_cselect_b64 s[8:9], -1, 0
	s_cmpk_gt_i32 s36, 0x3ff
	s_cbranch_scc1 .LBB0_1667
	s_ashr_i32 s1, s36, 31
	s_lshr_b32 s1, s1, 29
	s_add_i32 s1, s36, s1
	s_ashr_i32 s10, s1, 3
	s_and_b32 s1, s1, -8
	s_sub_i32 s1, s36, s1
	s_cmp_lt_i32 s1, 0
	s_movk_i32 s11, 0x81
	s_cselect_b32 s11, s11, 0x80
	s_mul_i32 s1, s11, s1
	s_add_i32 s1, s1, s10
	s_ashr_i32 s10, s1, 31
	s_lshr_b32 s10, s10, 27
	s_add_i32 s10, s1, s10
	s_ashr_i32 s11, s10, 5
	s_lshl_b32 s12, s11, 3
	s_sub_i32 s11, 0x100, s12
	s_min_u32 s13, s11, 8
	s_andn2_b32 s10, s10, 31
	s_sub_i32 s1, s1, s10
	v_cvt_f32_ubyte0_e32 v1, s13
	v_cvt_f32_i32_e32 v0, s1
	v_rcp_iflag_f32_e32 v2, v1
	s_ashr_i32 s10, s1, 30
	s_or_b32 s14, s10, 1
	v_mul_f32_e32 v2, v0, v2
	v_trunc_f32_e32 v2, v2
	v_fma_f32 v0, -v2, v1, v0
	v_cvt_i32_f32_e32 v2, v2
	v_cmp_ge_f32_e64 s[10:11], |v0|, v1
	s_and_b64 s[10:11], s[10:11], exec
	s_cselect_b32 s10, s14, 0
	v_readfirstlane_b32 s11, v2
	s_add_i32 s10, s11, s10
	s_sext_i32_i8 s60, s10
	s_mul_i32 s10, s10, s13
	s_sub_i32 s1, s1, s10
	s_sext_i32_i8 s1, s1
	s_add_i32 s34, s12, s1

; #define PG8_BAR __builtin_amdgcn_s_barrier()
; template <class Epi, class Sched, bool ALIGN_EPI = false, bool SP2 = false>
; __device__ __forceinline__ void gemm_phase(PG8_LAS unsigned char* lds, const Gemm g, const Sched& S, const Epi& E) {
;     ...
; #pragma unroll
;     for (int i = 0; i < 2; ++i) { int R, C; stage_rc(tid * 16 + i * 8192, R, C); const int Rb = Epi::PERM ? ((R & ~31) + perm32(R & 31)) : R;
;         voffA[i] = (unsigned)(R * g.lda + C) * 2u; voffB[i] = (unsigned)(Rb * K + C) * 2u; }
;     const size_t kstep = (size_t)(BK * 2);
;     const size_t hstepA = (size_t)HALF * g.lda * 2, hstepB = (size_t)HALF * K * 2;
;     const size_t tstepA = 2 * hstepA, tstepB = 2 * hstepB;
;     const unsigned ldsw = (unsigned)wid * 1024u;
;     const int aoff = lds_byte(wr * 64 + fr, fq * 8), boff = lds_byte(wc * 32 + fr, fq * 8);
;     ...
;     Unit cur, nxt; int ui = 0;
;     if (!S.next(0, cur)) return;
;     f32x4 acc[2][2][4][2];
; #pragma unroll
;     for (int a = 0; a < 2; ++a)
; #pragma unroll
;         for (int b = 0; b < 2; ++b)
; #pragma unroll
;             for (int m = 0; m < 4; ++m)
; #pragma unroll
;                 for (int n = 0; n < 2; ++n) acc[a][b][m][n] = (f32x4){0.f, 0.f, 0.f, 0.f};
;     bf16x8 At[4][2], B0[2][2], B1[2][2];
;     const char* cA = (cur.pm < g.pm_split) ? (const char*)g.A + (size_t)cur.pm * tstepA : (const char*)g.A2 + (size_t)(cur.pm - g.pm_split) * tstepA; const char* cB = (const char*)g.Bt + (size_t)cur.pn * tstepB;
;     S.a_ready(cur);
;     if constexpr (SP2) {
;         PG8_STAGE(PG8_SB(0, 0), cB, voffB); PG8_STAGE(PG8_SB(0, 1), cB + hstepB, voffB); PG8_STAGE(PG8_SA(0, 0), cA, voffA); PG8_STAGE(PG8_SA(0, 1), cA + hstepA, voffA);
;         if (wr == 1) PG8_BAR;
;         PG8_WAIT_V(2); PG8_BAR;
;         PG8_STAGE(PG8_SB(1, 0), cB + kstep, voffB); PG8_STAGE(PG8_SA(1, 0), cA + kstep, voffA); PG8_STAGE(PG8_SB(1, 1), cB + hstepB + kstep, voffB);
;         PG8_WAIT_V(6); PG8_BAR;
;     } else {
;         PG8_STAGE(PG8_SB(0, 0), cB, voffB); PG8_STAGE(PG8_SA(0, 0), cA, voffA); PG8_STAGE(PG8_SB(0, 1), cB + hstepB, voffB); PG8_STAGE(PG8_SA(0, 1), cA + hstepA, voffA);
;         if (wr == 1) PG8_BAR;
;         PG8_WAIT_V(4); PG8_BAR;
;         PG8_STAGE(PG8_SB(1, 0), cB + kstep, voffB); PG8_STAGE(PG8_SA(1, 0), cA + kstep, voffA); PG8_STAGE(PG8_SB(1, 1), cB + hstepB + kstep, voffB);
;         PG8_WAIT_V(6); PG8_BAR;
.Lm1_p7l1:
	v_ashrrev_i32_e32 v1, 31, v12
	v_lshrrev_b32_e32 v1, 26, v1
	v_add_u32_e32 v1, v12, v1
	v_ashrrev_i32_e32 v13, 6, v1
	v_bfe_i32 v1, v12, 27, 1
	v_lshlrev_b32_e32 v0, 4, v12
	v_lshrrev_b32_e32 v1, 22, v1
	v_add_u32_e32 v1, v0, v1
	v_and_b32_e32 v1, 0xfffffc00, v1
	v_sub_u32_e32 v1, v0, v1
	v_lshrrev_b32_e32 v2, 4, v1
	v_bitop3_b32 v1, v2, v1, 32 bitop3:0x6c
	v_ashrrev_i32_e32 v3, 31, v1
	v_lshrrev_b32_e32 v3, 26, v3
	v_lshlrev_b32_e32 v2, 3, v13
	v_add_u32_e32 v3, v1, v3
	v_and_b32_e32 v2, -16, v2
	v_ashrrev_i32_e32 v14, 6, v3
	v_and_b32_e32 v3, 0xc0, v3
	v_add_u32_e32 v2, v14, v2
	s_waitcnt lgkmcnt(0)
	v_lshlrev_b32_e32 v4, 5, v13
	v_sub_u32_e32 v1, v1, v3
	v_mov_b32_e32 v3, 1
	v_and_b32_e32 v15, 32, v4
	v_ashrrev_i16_sdwa v1, v3, sext(v1) dst_sel:DWORD dst_unused:UNUSED_PAD src0_sel:DWORD src1_sel:BYTE_0
	v_lshlrev_b32_e32 v4, 1, v2
	v_lshrrev_b32_e32 v5, 2, v2
	v_and_b32_e32 v6, 3, v14
	s_mov_b32 s1, 0x7fffffe0
	v_bfe_i32 v16, v1, 0, 16
	v_and_b32_e32 v4, 24, v4
	v_and_b32_e32 v5, 4, v5
	v_and_or_b32 v6, v2, s1, v6
	s_movk_i32 s24, 0xb00
	v_add_u32_e32 v1, v15, v16
	v_or3_b32 v4, v6, v5, v4
	v_mul_lo_u32 v2, v2, s24
	v_add_lshl_u32 v128, v1, v2, 1
	v_mul_lo_u32 v2, v4, s0
	v_add_u32_e32 v0, 0x2000, v0
	v_add_lshl_u32 v130, v2, v1, 1
	v_ashrrev_i32_e32 v1, 31, v0
	v_lshrrev_b32_e32 v1, 22, v1
	v_add_u32_e32 v1, v0, v1
	v_ashrrev_i32_e32 v17, 10, v1
	v_mul_i32_i24_e32 v1, 0x400, v17
	v_sub_u32_e32 v0, v0, v1
	v_lshrrev_b32_e32 v1, 4, v0
	v_bitop3_b32 v0, v1, v0, 32 bitop3:0x6c
	v_ashrrev_i32_e32 v2, 31, v0
	v_lshrrev_b32_e32 v2, 26, v2
	s_add_u32 s37, s2, 0x14200000
	v_lshlrev_b32_e32 v1, 3, v17
	v_add_u32_e32 v2, v0, v2
	s_addc_u32 s38, s3, 0
	v_and_b32_e32 v1, -16, v1
	v_ashrrev_i32_e32 v19, 6, v2
	v_lshlrev_b32_e32 v4, 5, v17
	s_add_u32 s39, s2, 0x2ba0000
	v_add_u32_e32 v1, v19, v1
	v_and_b32_e32 v18, 32, v4
	v_and_b32_e32 v4, 3, v19
	s_addc_u32 s40, s3, 0
	s_ashr_i32 s20, s22, 6
	v_and_or_b32 v4, v1, s1, v4
	s_ashr_i32 s1, s0, 31
	s_ashr_i32 s41, s22, 8
	s_lshl_b64 s[8:9], s[0:1], 8
	s_lshl_b64 s[10:11], s[0:1], 9
	s_lshl_b32 s42, s20, 10
	s_add_i32 s12, s34, 0xffffff76
	s_ashr_i32 s13, s34, 31
	s_cmpk_lt_i32 s34, 0x8a
	s_cselect_b32 s12, s34, s12
	s_cselect_b32 s13, s13, 0
	s_mul_i32 s13, s13, 0x160000
	s_mul_hi_u32 s16, s12, 0x160000
	s_cselect_b32 s14, s38, s7
	s_cselect_b32 s15, s37, s6
	s_sub_u32 s84, s92, 0xa140000
	s_subb_u32 s85, s93, 0
	s_cmpk_gt_i32 s34, 0xff
	s_cselect_b32 s15, s84, s15
	s_cselect_b32 s14, s85, s14
	s_add_i32 s16, s16, s13
	s_mul_i32 s12, s12, 0x160000
	s_add_u32 s28, s15, s12
	s_addc_u32 s29, s14, s16
	s_ashr_i32 s12, s60, 31
	s_mul_i32 s12, s10, s12
	s_mul_hi_u32 s13, s10, s60
	s_add_i32 s14, s13, s12
	s_lshr_b64 s[12:13], s[0:1], 23
	v_and_b32_e32 v2, 0xc0, v2
	s_mul_i32 s12, s12, s60
	v_sub_u32_e32 v0, v0, v2
	s_add_i32 s14, s14, s12
	s_mul_i32 s12, s10, s60
	v_ashrrev_i16_sdwa v0, v3, sext(v0) dst_sel:DWORD dst_unused:UNUSED_PAD src0_sel:DWORD src1_sel:BYTE_0
	v_lshlrev_b32_e32 v2, 1, v1
	v_lshrrev_b32_e32 v3, 2, v1
	s_add_u32 s30, s39, s12
	v_bfe_i32 v20, v0, 0, 16
	v_and_b32_e32 v2, 24, v2
	v_and_b32_e32 v3, 4, v3
	s_addc_u32 s31, s40, s14
	s_add_i32 s43, s42, 0
	v_add_u32_e32 v0, v18, v20
	v_or3_b32 v2, v4, v3, v2
	v_mul_lo_u32 v1, v1, s24
	s_add_i32 m0, s43, 0x10000
	v_add_lshl_u32 v132, v0, v1, 1
	v_mul_lo_u32 v1, v2, s0
	global_load_lds_dwordx4 v130, s[30:31]
	s_add_i32 m0, s43, 0x12000
	v_add_lshl_u32 v134, v1, v0, 1
	s_add_u32 s12, s30, s8
	global_load_lds_dwordx4 v134, s[30:31]
	s_addc_u32 s13, s31, s9
	s_add_i32 m0, s43, 0x14000
	s_add_i32 s44, s43, 0x2000
	global_load_lds_dwordx4 v130, s[12:13]
	s_add_i32 m0, s43, 0x16000
	s_add_u32 s14, s28, 0xb0000
	global_load_lds_dwordx4 v134, s[12:13]
	s_mov_b32 m0, s43
	s_addc_u32 s15, s29, 0
	global_load_lds_dwordx4 v128, s[28:29]
	s_mov_b32 m0, s44
	s_add_i32 s45, s43, 0x4000
	global_load_lds_dwordx4 v132, s[28:29]
	s_mov_b32 m0, s45
	s_add_i32 s46, s43, 0x6000
	global_load_lds_dwordx4 v128, s[14:15]
	s_mov_b32 m0, s46
	v_mov_b32_e32 v131, 0
	global_load_lds_dwordx4 v132, s[14:15]
	v_mov_b32_e32 v135, v131
	v_mov_b32_e32 v129, v131
	v_mov_b32_e32 v133, v131
	s_cmp_eq_u32 s41, 1
	s_mov_b32 s47, 0
	v_lshl_add_u64 v[8:9], s[30:31], 0, v[130:131]
	v_lshl_add_u64 v[4:5], s[30:31], 0, v[134:135]
	v_lshl_add_u64 v[2:3], s[12:13], 0, v[130:131]
	v_lshl_add_u64 v[0:1], s[12:13], 0, v[134:135]
	v_lshl_add_u64 v[6:7], s[28:29], 0, v[128:129]
	s_cselect_b64 s[12:13], -1, 0
	s_cmp_lg_u32 s41, 1
	v_lshl_add_u64 v[10:11], s[28:29], 0, v[132:133]
	s_cbranch_scc1 .LBB0_1670
	s_barrier
.LBB0_1670:
	s_add_u32 s14, s2, 0xc100000
	s_addc_u32 s15, s3, 0
	s_add_u32 s16, s2, 0x3700000
	s_mov_b64 s[18:19], 0x80
	s_addc_u32 s17, s3, 0
	s_add_i32 m0, s43, 0x18000
	v_lshl_add_u64 v[8:9], v[8:9], 0, s[18:19]
	s_waitcnt vmcnt(2)
	s_barrier
	global_load_lds_dwordx4 v[8:9], off
	v_lshl_add_u64 v[4:5], v[4:5], 0, s[18:19]
	s_add_i32 m0, s43, 0x1a000
	s_add_i32 s48, s43, 0x8000
	global_load_lds_dwordx4 v[4:5], off
	v_lshl_add_u64 v[4:5], v[6:7], 0, s[18:19]
	s_mov_b32 m0, s48
	s_add_i32 s49, s43, 0xa000
	global_load_lds_dwordx4 v[4:5], off
	v_lshl_add_u64 v[4:5], v[10:11], 0, s[18:19]
	s_mov_b32 m0, s49
	v_lshl_add_u64 v[2:3], v[2:3], 0, s[18:19]
	global_load_lds_dwordx4 v[4:5], off
	s_add_i32 m0, s43, 0x1c000
	v_lshl_add_u64 v[0:1], v[0:1], 0, s[18:19]
	global_load_lds_dwordx4 v[2:3], off
	s_add_i32 m0, s43, 0x1e000
	v_and_b32_e32 v148, 15, v12
	global_load_lds_dwordx4 v[0:1], off
	s_lshr_b32 s1, s1, 26
	v_bfe_u32 v149, v12, 4, 2
	s_add_i32 s1, s0, s1
	v_lshlrev_b32_e32 v0, 6, v148
	v_lshlrev_b32_e32 v1, 2, v12
	s_and_b32 s50, s20, 3
	s_ashr_i32 s51, s1, 6
	v_lshl_or_b32 v0, v149, 4, v0
	s_lshl_b32 s1, s41, 13
	v_and_b32_e32 v1, 32, v1
	v_bitop3_b32 v2, v0, s1, v1 bitop3:0xde
	s_lshl_b32 s1, s50, 12
	v_bitop3_b32 v150, v0, s1, v1 bitop3:0xde
	v_lshrrev_b32_e32 v1, 1, v17
	v_mul_lo_u32 v0, v19, s24
	s_mov_b32 s2, 0xb000
	s_cmp_gt_i32 s0, 63
	v_mad_u64_u32 v[0:1], s[0:1], v1, s2, v[0:1]
	v_or_b32_e32 v0, v0, v18
	v_add_lshl_u32 v0, v0, v20, 1
	v_mov_b32_e32 v1, v131
	s_mov_b64 s[0:1], 0xb0080
	v_lshl_add_u64 v[136:137], v[0:1], 0, s[0:1]
	v_lshrrev_b32_e32 v1, 1, v13
	v_mul_lo_u32 v0, v14, s24
	v_mad_u64_u32 v[0:1], s[2:3], v1, s2, v[0:1]
	s_cselect_b64 s[20:21], -1, 0
	s_add_i32 s52, s51, -2
	v_or_b32_e32 v0, v0, v15
	s_waitcnt vmcnt(6)
	s_cmpk_lt_u32 s22, 0x100
	v_add_lshl_u32 v0, v0, v16, 1
	v_mov_b32_e32 v1, v131
	s_cselect_b64 s[22:23], -1, 0
	v_lshl_add_u64 v[138:139], v[0:1], 0, s[0:1]
	s_add_i32 s56, 0, 0x10000
	s_add_i32 s57, 0, 0x14000
	v_mbcnt_lo_u32_b32 v0, -1, 0
	s_ashr_i32 s53, s33, 31
	s_ashr_i32 s54, s36, 31
	v_mov_b64_e32 v[140:141], 0x400
	v_mov_b64_e32 v[142:143], 0x3ff
	s_movk_i32 s55, 0x81
	v_add_u32_e32 v151, s56, v150
	v_add_u32_e32 v152, s57, v150
	v_add_u32_e32 v153, 0, v2
	v_mbcnt_hi_u32_b32 v154, -1, v0
	s_barrier
	s_waitcnt vmcnt(0)
	s_branch .LBB0_1673

;     __host__ __device__ bool next(int i, Unit& u) const {
;         const long L = (long)i * G + c; if (L >= nwg) return false;
;         int wgid = (int)L; { const int q = nwg / NXCD, r = nwg % NXCD, xcd = wgid % NXCD, off = wgid / NXCD; wgid = (xcd < r ? xcd * (q + 1) : r * (q + 1) + (xcd - r) * q) + off; }
;         const int nig = WGM * nN, gid = wgid / nig, fm = gid * WGM, gsz = (nM - fm) < WGM ? (nM - fm) : WGM;
;         u.pm = fm + ((wgid % nig) % gsz); u.pn = (wgid % nig) / gsz; return true;
.LBB0_1673:
	s_add_i32 s47, s47, 1
	s_mul_i32 s0, s47, s53
	s_mul_hi_u32 s1, s47, s33
	s_add_i32 s1, s1, s0
	s_mul_i32 s0, s47, s33
	s_add_u32 s2, s0, s36
	s_addc_u32 s3, s1, s54
	v_cmp_gt_i64_e32 vcc, s[2:3], v[142:143]
	v_cmp_lt_i64_e64 s[0:1], s[2:3], v[140:141]
	s_cbranch_vccnz .LBB0_1675
	s_ashr_i32 s3, s2, 31
	s_lshr_b32 s3, s3, 29
	s_add_i32 s3, s2, s3
	s_ashr_i32 s24, s3, 3
	s_and_b32 s3, s3, -8
	s_sub_i32 s2, s2, s3
	s_cmp_lt_i32 s2, 0
	s_cselect_b32 s3, s55, 0x80
	s_mul_i32 s2, s3, s2
	s_add_i32 s2, s2, s24
	s_ashr_i32 s3, s2, 31
	s_lshr_b32 s3, s3, 27
	s_add_i32 s3, s2, s3
	s_ashr_i32 s24, s3, 5
	s_lshl_b32 s24, s24, 3
	s_sub_i32 s25, 0x100, s24
	s_min_i32 s25, s25, 8
	s_abs_i32 s26, s25
	v_cvt_f32_u32_e32 v0, s26
	s_sub_i32 s35, 0, s26
	s_andn2_b32 s3, s3, 31
	s_sub_i32 s2, s2, s3
	v_rcp_iflag_f32_e32 v0, v0
	s_abs_i32 s3, s2
	s_xor_b32 s27, s2, s25
	s_ashr_i32 s27, s27, 31
	v_mul_f32_e32 v0, 0x4f7ffffe, v0
	v_cvt_u32_f32_e32 v0, v0
	s_nop 0
	v_readfirstlane_b32 s58, v0
	s_mul_i32 s35, s35, s58
	s_mul_hi_u32 s35, s58, s35
	s_add_i32 s58, s58, s35
	s_mul_hi_u32 s35, s3, s58
	s_mul_i32 s58, s35, s26
	s_sub_i32 s3, s3, s58
	s_add_i32 s59, s35, 1
	s_sub_i32 s58, s3, s26
	s_cmp_ge_u32 s3, s26
	s_cselect_b32 s35, s59, s35
	s_cselect_b32 s3, s58, s3
	s_add_i32 s58, s35, 1
	s_cmp_ge_u32 s3, s26
	s_cselect_b32 s3, s58, s35
	s_xor_b32 s3, s3, s27
	s_sub_i32 s58, s3, s27
	s_mul_i32 s3, s58, s25
	s_sub_i32 s2, s2, s3
	s_add_i32 s59, s2, s24

; __device__ __forceinline__ unsigned xb_ld(unsigned* p)              { return __hip_atomic_load(p, __ATOMIC_RELAXED, __HIP_MEMORY_SCOPE_AGENT); }
; __device__ __forceinline__ unsigned xb_add(unsigned* p, unsigned v) { return __hip_atomic_fetch_add(p, v, __ATOMIC_RELAXED, __HIP_MEMORY_SCOPE_AGENT); }
; #define XB_SPIN(cond, bar) do { unsigned _sp = 0; while (cond) { __builtin_amdgcn_s_sleep(1); \
;     if ((++_sp & 255u) == 0u) { if (xb_ld(&(bar)[XB_TMO])) break; if (_sp > XB_SPIN_CAP) { atomicAdd(&(bar)[XB_TMO], 1u); break; } } } } while (0)
; __device__ __forceinline__ void xcd_barrier(const XcdBarrier& b) {
;     asm volatile("s_waitcnt vmcnt(0)" ::: "memory");
;     __syncthreads();
;     if (threadIdx.x == 0) {
;         unsigned* bar = b.bar;
;         __builtin_amdgcn_s_waitcnt(0);
;         unsigned nloc = b.st[0], nx = b.st[1];
;         if (nloc == 0u) { xcd_barrier_complete(bar, b.x, nloc, nx); b.st[0] = nloc; b.st[1] = nx; }
;         const unsigned old = xb_add(&bar[XB_XSUB(b.x)], 1u);
;         const unsigned gen = old / nloc;
;         if (old + 1u == (gen + 1u) * nloc) {
;             __builtin_amdgcn_fence(__ATOMIC_RELEASE, "agent");
;             asm volatile("s_waitcnt vmcnt(0)" ::: "memory");
;             const unsigned og = xb_add(&bar[XB_TOP], 1u);
;             const unsigned tg = og / nx;
;             if (og + 1u == (tg + 1u) * nx) xb_add(&bar[XB_TOPGEN], 1u);
;             else XB_SPIN(xb_ld(&bar[XB_TOPGEN]) == tg, bar);
;             __builtin_amdgcn_fence(__ATOMIC_ACQUIRE, "agent");
;             xb_add(&bar[XB_XGEN(b.x)], 1u);
;             asm volatile("s_waitcnt vmcnt(0)" ::: "memory");
;         } else {
;             XB_SPIN(xb_ld(&bar[XB_XGEN(b.x)]) == gen, bar);
;             __builtin_amdgcn_fence(__ATOMIC_ACQUIRE, "agent");
;             asm volatile("s_waitcnt vmcnt(0)" ::: "memory");
;         }
;     }
;     __syncthreads();
.LBB0_1707:
	s_cmp_gt_i32 s95, 16
	s_cselect_b64 s[0:1], -1, 0
	s_and_b64 s[2:3], s[4:5], s[0:1]
	s_andn2_b64 vcc, exec, s[2:3]
	s_cbranch_vccnz .LBB0_1752
	v_readfirstlane_b32 vcc_lo, v251
	s_cmp_lg_u32 vcc_lo, 0
	s_cbranch_scc1 .LBB0_1752
	s_waitcnt vmcnt(0)
	s_waitcnt vmcnt(0) lgkmcnt(0)
	s_barrier
	s_mov_b64 s[2:3], exec
	v_readlane_b32 s4, v250, 0
	v_readlane_b32 s5, v250, 1
	s_and_b64 s[4:5], s[2:3], s[4:5]
	s_mov_b64 exec, s[4:5]
	s_cbranch_execz .LBB0_1751
	s_add_i32 s4, 0, 0x23fc0
	v_mov_b32_e32 v0, s4
	s_waitcnt vmcnt(0) expcnt(0) lgkmcnt(0)
	ds_read_b32 v2, v0
	s_add_i32 s4, 0, 0x23fc4
	v_mov_b32_e32 v0, s4
	ds_read_b32 v0, v0
	s_waitcnt lgkmcnt(1)
	v_cmp_ne_u32_e32 vcc, 0, v2
	s_cbranch_vccnz .LBB0_1722
	s_add_u32 s4, s72, 0x1000
	s_addc_u32 s5, s73, 0
	s_add_u32 s6, s72, 0x1100
	s_addc_u32 s7, s73, 0
	s_add_u32 s8, s72, 0x1200
	s_addc_u32 s9, s73, 0
	s_mul_i32 s18, s97, s71
	s_add_u32 s10, s72, 0x1300
	s_mul_i32 s18, s18, s96
	s_addc_u32 s11, s73, 0
	s_mov_b32 s19, 1
	v_mov_b32_e32 v16, 0
	s_branch .LBB0_1712

; __device__ __forceinline__ void nr_pass(bf16* X, const bf16* Y, const float* SSQ, float* ssqX, const float* g, float* out  , int gw, int NGW, int lane) {
;     f32x4 gv[4];
; #pragma unroll
;     for (int j = 0; j < 4; ++j) gv[j] = *((const f32x4*)g + lane + 64 * j);
;     for (int r = gw; r < M_REAL; r += NGW) {
;         const float part = SSQ[(size_t)r * 32 + (lane & 31)];
;         const float s = rsqrtf(half_sum32(part) * (1.0f / 1024.0f) + EPS);
;         v2u* x8 = (v2u*)(X + (size_t)r * 1024) + lane; const v2u* y8 = (const v2u*)(Y + (size_t)r * 1024) + lane;
.LBB0_1752:
	v_readfirstlane_b32 vcc_lo, v251
	v_mov_b32_e32 v251, 1
	s_cmp_eq_u32 vcc_lo, 0
	s_cbranch_scc1 .Lre_p7l1
	s_cmp_lt_i32 s94, 17
	s_cselect_b64 s[4:5], -1, 0
	s_and_b64 s[0:1], s[4:5], s[0:1]
	s_andn2_b64 vcc, exec, s[0:1]
	s_cbranch_vccnz .LBB0_1768
	s_mov_b64 s[0:1], s[90:91]
	s_mov_b32 s2, s96
	v_readfirstlane_b32 s0, v183
	s_lshr_b32 s0, s0, 6
	s_lshl_b32 s1, s70, 3
	s_mov_b32 s63, 0x10120
	s_cmp_lt_u32 s70, 8
	s_cbranch_scc1 .Lnr_tail_p7l1
	s_sub_i32 s1, s1, 64
	s_sub_i32 s2, s2, 8
	s_mov_b32 s63, 0x10000
	s_branch .Lnr_go_p7l1
.Lnr_tail_p7l1:
	s_waitcnt vmcnt(0) lgkmcnt(0)
	s_barrier
	s_cmp_lg_u32 s0, 0
	s_cbranch_scc1 .Lnr_tsd_p7l1
	s_mov_b64 exec, 1
	buffer_wbl2 sc1
	s_waitcnt vmcnt(0)
	v_mov_b32_e32 v252, 0
	v_mov_b32_e32 v253, 1
	global_atomic_add v252, v253, s[92:93] offset:2816
	s_waitcnt vmcnt(0)
.Lnr_tspin_p7l1:
	global_load_dword v254, v252, s[92:93] offset:2816 sc1
	s_waitcnt vmcnt(0)
	v_readfirstlane_b32 vcc_lo, v254
	s_cmp_ge_u32 vcc_lo, 8
	s_cbranch_scc1 .Lnr_tspun_p7l1
	s_sleep 2
	s_branch .Lnr_tspin_p7l1

; __device__ __forceinline__ unsigned pk2(float lo, float hi) { return f2bf(lo) | (f2bf(hi) << 16); }
; __device__ __forceinline__ void nr_pass(bf16* X, const bf16* Y, const float* SSQ, float* ssqX, const float* g, float* out  , int gw, int NGW, int lane) {
;     f32x4 gv[4];
; #pragma unroll
;     for (int j = 0; j < 4; ++j) gv[j] = *((const f32x4*)g + lane + 64 * j);
;     for (int r = gw; r < M_REAL; r += NGW) {
;         const float part = SSQ[(size_t)r * 32 + (lane & 31)];
;         const float s = rsqrtf(half_sum32(part) * (1.0f / 1024.0f) + EPS);
;         v2u* x8 = (v2u*)(X + (size_t)r * 1024) + lane; const v2u* y8 = (const v2u*)(Y + (size_t)r * 1024) + lane;
;         f32x4 v[4]; float s2 = 0.f;
; #pragma unroll
;         for (int j = 0; j < 4; ++j) { const v2u xv = x8[64 * j], yv = __builtin_nontemporal_load(&y8[64 * j]);
;             v[j].x = bflo(xv.x) + bflo(yv.x) * s * gv[j].x; v[j].y = bfhi(xv.x) + bfhi(yv.x) * s * gv[j].y;
;             v[j].z = bflo(xv.y) + bflo(yv.y) * s * gv[j].z; v[j].w = bfhi(xv.y) + bfhi(yv.y) * s * gv[j].w;
;             s2 += (v[j].x * v[j].x + v[j].y * v[j].y) + (v[j].z * v[j].z + v[j].w * v[j].w); }
;         if (out == nullptr) {
;             s2 = wave_sum(s2);
; #pragma unroll
;             for (int j = 0; j < 4; ++j) x8[64 * j] = (v2u){pk2(v[j].x, v[j].y), pk2(v[j].z, v[j].w)};
;             if (lane == 0) ssqX[r] = s2;
;         } else {
;             int pos; size_t orow;
;             if (r < ROWS_P) { const int sq = r / L_P; pos = r - sq * L_P; orow = (size_t)sq * 2048 + (pos - 16); }
;             else { const int q = r - ROWS_P, sq = q / L_S; pos = q - sq * L_S; orow = (size_t)NSEQ_P * 2048 + (size_t)sq * 16384 + (pos - 16); }
;             if (pos >= 16) { f32x4* o = (f32x4*)(out + orow * 1024) + lane;
; #pragma unroll
;                 for (int j = 0; j < 4; ++j) o[64 * j] = v[j]; }
;         }
.Lnr_tsd_p7l1:
	s_barrier
	s_add_i32 s1, s1, 0x10000
	s_mov_b32 s2, 8
.Lnr_go_p7l1:
	s_add_i32 s28, s1, s0
	s_cmp_ge_i32 s28, s63
	s_cbranch_scc1 .LBB0_1768
	v_ashrrev_i32_e32 v183, 31, v182
	v_lshlrev_b64 v[16:17], 4, v[182:183]
	v_lshl_add_u64 v[12:13], s[88:89], 0, v[16:17]
	s_mov_b64 s[6:7], 0x1000
	v_lshl_add_u64 v[14:15], v[12:13], 0, s[6:7]
	v_add_co_u32_e32 v12, vcc, 0x1000, v12
	global_load_dwordx4 v[0:3], v[14:15], off offset:1024
	s_waitcnt lgkmcnt(0)
	global_load_dwordx4 v[4:7], v[14:15], off offset:2048
	global_load_dwordx4 v[8:11], v[14:15], off offset:3072
	v_addc_co_u32_e32 v13, vcc, 0, v13, vcc
	global_load_dwordx4 v[12:15], v[12:13], off
	v_mbcnt_lo_u32_b32 v18, -1, 0
	v_mbcnt_hi_u32_b32 v18, -1, v18
	s_lshl_b32 s6, s2, 3
	v_and_b32_e32 v19, 64, v18
	s_cmp_lg_u64 s[90:91], 0
	v_xor_b32_e32 v21, 1, v18
	v_add_u32_e32 v19, 64, v19
	v_xor_b32_e32 v22, 2, v18
	s_cselect_b64 s[12:13], -1, 0
	s_add_i32 s30, s28, 0xffff7f00
	s_ashr_i32 s7, s0, 31
	s_ashr_i32 s8, s1, 31
	v_cmp_lt_i32_e32 vcc, v21, v19
	v_xor_b32_e32 v23, 4, v18
	s_add_u32 s0, s0, s1
	v_cndmask_b32_e32 v21, v18, v21, vcc
	v_cmp_lt_i32_e32 vcc, v22, v19
	v_xor_b32_e32 v24, 8, v18
	s_addc_u32 s1, s7, s8
	v_cndmask_b32_e32 v22, v18, v22, vcc
	v_cmp_lt_i32_e32 vcc, v23, v19
	v_xor_b32_e32 v25, 16, v18
	s_lshl_b64 s[14:15], s[0:1], 2
	v_cndmask_b32_e32 v23, v18, v23, vcc
	v_cmp_lt_i32_e32 vcc, v24, v19
	v_xor_b32_e32 v26, 32, v18
	s_add_u32 s31, s14, 0x3f80000
	v_cndmask_b32_e32 v24, v18, v24, vcc
	v_cmp_lt_i32_e32 vcc, v25, v19
	v_and_b32_e32 v20, 31, v182
	s_addc_u32 s33, s15, 0
	v_cndmask_b32_e32 v25, v18, v25, vcc
	v_cmp_lt_i32_e32 vcc, v26, v19
	s_lshl_b64 s[16:17], s[0:1], 11
	s_lshl_b64 s[0:1], s[0:1], 7
	s_mov_b64 s[20:21], 0x3700000
	v_cndmask_b32_e32 v18, v18, v26, vcc
	v_lshlrev_b32_e32 v41, 2, v21
	s_ashr_i32 s7, s6, 31
	v_lshl_or_b32 v20, v20, 2, s0
	v_mov_b32_e32 v21, s1
	s_mov_b32 s9, 0
	v_cmp_eq_u32_e64 s[2:3], 0, v182
	v_mov_b32_e32 v40, 0x358637bd
	s_mov_b32 s29, 0x800000
	s_mov_b64 s[10:11], 0x4000000
	v_lshl_add_u64 v[16:17], s[90:91], 0, v[16:17]
	v_lshlrev_b32_e32 v42, 2, v22
	v_lshlrev_b32_e32 v43, 2, v23
	v_lshlrev_b32_e32 v44, 2, v24
	v_lshlrev_b32_e32 v45, 2, v25
	v_lshlrev_b32_e32 v46, 2, v18
	s_lshl_b64 s[14:15], s[6:7], 2
	v_lshl_add_u64 v[18:19], v[182:183], 3, s[16:17]
	s_lshl_b64 s[16:17], s[6:7], 11
	s_lshl_b64 s[18:19], s[6:7], 7
	v_lshl_add_u64 v[20:21], v[20:21], 0, s[20:21]
	s_brev_b32 s7, 32
	s_mov_b32 s34, 0xc100000
	s_mov_b64 s[20:21], 0x4000200
	s_mov_b64 s[22:23], 0x4000400
	s_mov_b64 s[24:25], 0x4000600
	s_mov_b32 s35, 0xc000
	s_movk_i32 s36, 0x7fff
	v_mov_b32_e32 v47, 0
	v_mov_b32_e32 v48, 1
	s_waitcnt vmcnt(0)
	v_mov_b32_e32 v22, v1
	v_mov_b32_e32 v23, v3
	v_mov_b32_e32 v1, v2
	v_mov_b32_e32 v2, v5
	v_mov_b32_e32 v3, v7
	v_mov_b32_e32 v5, v6
	v_mov_b32_e32 v6, v9
	v_mov_b32_e32 v7, v11
	v_mov_b32_e32 v9, v10
	v_mov_b32_e32 v10, v13
	v_mov_b32_e32 v11, v15
	v_mov_b32_e32 v13, v14
	s_branch .LBB0_1757

; __device__ __forceinline__ unsigned pk2(float lo, float hi) { return f2bf(lo) | (f2bf(hi) << 16); }
; __device__ __forceinline__ void nr_pass(bf16* X, const bf16* Y, const float* SSQ, float* ssqX, const float* g, float* out  , int gw, int NGW, int lane) {
;     ...
;     for (int r = gw; r < M_REAL; r += NGW) {
;         const float part = SSQ[(size_t)r * 32 + (lane & 31)];
;         const float s = rsqrtf(half_sum32(part) * (1.0f / 1024.0f) + EPS);
;         v2u* x8 = (v2u*)(X + (size_t)r * 1024) + lane; const v2u* y8 = (const v2u*)(Y + (size_t)r * 1024) + lane;
;         f32x4 v[4]; float s2 = 0.f;
; #pragma unroll
;         for (int j = 0; j < 4; ++j) { const v2u xv = x8[64 * j], yv = __builtin_nontemporal_load(&y8[64 * j]);
;             v[j].x = bflo(xv.x) + bflo(yv.x) * s * gv[j].x; v[j].y = bfhi(xv.x) + bfhi(yv.x) * s * gv[j].y;
;             v[j].z = bflo(xv.y) + bflo(yv.y) * s * gv[j].z; v[j].w = bfhi(xv.y) + bfhi(yv.y) * s * gv[j].w;
;             s2 += (v[j].x * v[j].x + v[j].y * v[j].y) + (v[j].z * v[j].z + v[j].w * v[j].w); }
;         if (out == nullptr) {
;             s2 = wave_sum(s2);
; #pragma unroll
;             for (int j = 0; j < 4; ++j) x8[64 * j] = (v2u){pk2(v[j].x, v[j].y), pk2(v[j].z, v[j].w)};
;             if (lane == 0) ssqX[r] = s2;
;         } else {
;             int pos; size_t orow;
;             if (r < ROWS_P) { const int sq = r / L_P; pos = r - sq * L_P; orow = (size_t)sq * 2048 + (pos - 16); }
;             else { const int q = r - ROWS_P, sq = q / L_S; pos = q - sq * L_S; orow = (size_t)NSEQ_P * 2048 + (size_t)sq * 16384 + (pos - 16); }
;             if (pos >= 16) { f32x4* o = (f32x4*)(out + orow * 1024) + lane;
; #pragma unroll
;                 for (int j = 0; j < 4; ++j) o[64 * j] = v[j]; }
;         }
.LBB0_1756:
	s_add_i32 s30, s30, s6
	s_add_i32 s28, s28, s6
	s_add_i32 s0, s30, 0x8100
	s_add_u32 s31, s31, s14
	s_addc_u32 s33, s33, s15
	v_lshl_add_u64 v[18:19], v[18:19], 0, s[16:17]
	s_cmp_lt_i32 s0, s63
	v_lshl_add_u64 v[20:21], v[20:21], 0, s[18:19]
	s_cbranch_scc0 .LBB0_1768
